# stack of all validated edits: late stagger barrier (per tile and at phase entry), saddr LDS-DMA, norm and prologue row prefetch, early FFN-up epilogue start, canonicalize removal, prologue row mirrori
# baseline (speedup 1.0000x reference)
.LBB0_236:
	v_readlane_b32 s12, v255, 18
	v_readlane_b32 s13, v255, 19
	s_andn2_b64 vcc, exec, s[12:13]
	s_cbranch_vccnz .LBB0_241
	v_and_b32_e32 v0, 64, v4
	v_add_u32_e32 v0, 64, v0
	v_xor_b32_e32 v1, 1, v4
	v_cmp_lt_i32_e32 vcc, v1, v0
	v_readlane_b32 s66, v255, 30
	v_readlane_b32 s68, v255, 28
	v_cndmask_b32_e32 v1, v4, v1, vcc
	v_lshlrev_b32_e32 v16, 2, v1
	v_xor_b32_e32 v1, 2, v4
	v_cmp_lt_i32_e32 vcc, v1, v0
	v_readlane_b32 s67, v255, 31
	v_readlane_b32 s69, v255, 29
	v_cndmask_b32_e32 v1, v4, v1, vcc
	v_lshlrev_b32_e32 v17, 2, v1
	v_xor_b32_e32 v1, 4, v4
	v_cmp_lt_i32_e32 vcc, v1, v0
	s_nop 1
	v_cndmask_b32_e32 v1, v4, v1, vcc
	v_lshlrev_b32_e32 v18, 2, v1
	v_xor_b32_e32 v1, 8, v4
	v_cmp_lt_i32_e32 vcc, v1, v0
	s_nop 1
	v_cndmask_b32_e32 v1, v4, v1, vcc
	v_lshlrev_b32_e32 v19, 2, v1
	v_xor_b32_e32 v1, 16, v4
	v_cmp_lt_i32_e32 vcc, v1, v0
	s_nop 1
	v_cndmask_b32_e32 v1, v4, v1, vcc
	v_lshlrev_b32_e32 v20, 2, v1
	v_xor_b32_e32 v1, 32, v4
	v_cmp_lt_i32_e32 vcc, v1, v0
	s_nop 1
	v_cndmask_b32_e32 v0, v4, v1, vcc
	v_lshlrev_b32_e32 v21, 2, v0
	s_mov_b32 s57, 0
	s_sub_i32 s12, 0x7ff, s68
	s_sub_i32 s13, s12, s68
	s_mov_b32 s68, s12
	s_mov_b32 s12, s13
	s_ashr_i32 s13, s13, 31
	s_lshl_b64 s[12:13], s[12:13], 12
	s_add_u32 s66, s66, s12
	s_addc_u32 s67, s67, s13
	s_branch .LBB0_239

.Llsb_skip_9:
.LBB0_1243:
	ds_read_b128 v[150:153], v147
	ds_read_b128 v[154:157], v147 offset:1024
	ds_read_b128 v[158:161], v147 offset:2048
	ds_read_b128 v[162:165], v147 offset:3072
	ds_read_b128 v[166:169], v148
	ds_read_b128 v[170:173], v148 offset:1024
	ds_read_b128 v[174:177], v148 offset:2048
	ds_read_b128 v[178:181], v148 offset:3072
	s_add_u32 s24, s22, 0xfffc0080
	s_addc_u32 s25, s23, -1
	s_cmp_eq_u32 s51, 12
	s_cselect_b32 s27, s15, s25
	s_cselect_b32 s26, s47, s24
	s_cselect_b32 s25, s13, s50
	s_cselect_b32 s24, s48, s49
	s_add_i32 m0, s21, 0xc000
	ds_read_b128 v[182:185], v149
	ds_read_b128 v[186:189], v149 offset:1024
	ds_read_b128 v[190:193], v149 offset:2048
	ds_read_b128 v[194:197], v149 offset:3072
	ds_read_b128 v[198:201], v149 offset:4096
	ds_read_b128 v[206:209], v149 offset:5120
	ds_read_b128 v[210:213], v149 offset:6144
	ds_read_b128 v[214:217], v149 offset:7168
	global_load_lds_dwordx4 v136, s[22:23]
	s_add_i32 m0, s21, 0xe000
	s_nop 0
	global_load_lds_dwordx4 v138, s[22:23]
	s_waitcnt vmcnt(8)
	s_waitcnt lgkmcnt(0)
	s_barrier
	s_setprio 1
	s_waitcnt lgkmcnt(0)
	v_mfma_f32_16x16x32_bf16 v[124:127], v[150:153], v[182:185], v[124:127]
	v_mfma_f32_16x16x32_bf16 v[120:123], v[158:161], v[182:185], v[120:123]
	v_mfma_f32_16x16x32_bf16 v[108:111], v[150:153], v[190:193], v[108:111]
	v_mfma_f32_16x16x32_bf16 v[104:107], v[158:161], v[190:193], v[104:107]
	v_mfma_f32_16x16x32_bf16 v[92:95], v[150:153], v[198:201], v[92:95]
	v_mfma_f32_16x16x32_bf16 v[88:91], v[158:161], v[198:201], v[88:91]
	v_mfma_f32_16x16x32_bf16 v[76:79], v[150:153], v[210:213], v[76:79]
	v_mfma_f32_16x16x32_bf16 v[72:75], v[158:161], v[210:213], v[72:75]
	v_mfma_f32_16x16x32_bf16 v[124:127], v[154:157], v[186:189], v[124:127]
	v_mfma_f32_16x16x32_bf16 v[120:123], v[162:165], v[186:189], v[120:123]
	v_mfma_f32_16x16x32_bf16 v[108:111], v[154:157], v[194:197], v[108:111]
	v_mfma_f32_16x16x32_bf16 v[104:107], v[162:165], v[194:197], v[104:107]
	v_mfma_f32_16x16x32_bf16 v[92:95], v[154:157], v[206:209], v[92:95]
	v_mfma_f32_16x16x32_bf16 v[88:91], v[162:165], v[206:209], v[88:91]
	v_mfma_f32_16x16x32_bf16 v[76:79], v[154:157], v[214:217], v[76:79]
	v_mfma_f32_16x16x32_bf16 v[72:75], v[162:165], v[214:217], v[72:75]
	s_setprio 0
	s_setprio 1
	v_mfma_f32_16x16x32_bf16 v[116:119], v[166:169], v[182:185], v[116:119]
	v_mfma_f32_16x16x32_bf16 v[112:115], v[174:177], v[182:185], v[112:115]
	v_mfma_f32_16x16x32_bf16 v[100:103], v[166:169], v[190:193], v[100:103]
	v_mfma_f32_16x16x32_bf16 v[96:99], v[174:177], v[190:193], v[96:99]
	v_mfma_f32_16x16x32_bf16 v[84:87], v[166:169], v[198:201], v[84:87]
	v_mfma_f32_16x16x32_bf16 v[80:83], v[174:177], v[198:201], v[80:83]
	v_mfma_f32_16x16x32_bf16 v[68:71], v[166:169], v[210:213], v[68:71]
	v_mfma_f32_16x16x32_bf16 v[64:67], v[174:177], v[210:213], v[64:67]
	v_mfma_f32_16x16x32_bf16 v[116:119], v[170:173], v[186:189], v[116:119]
	v_mfma_f32_16x16x32_bf16 v[112:115], v[178:181], v[186:189], v[112:115]
	v_mfma_f32_16x16x32_bf16 v[100:103], v[170:173], v[194:197], v[100:103]
	v_mfma_f32_16x16x32_bf16 v[96:99], v[178:181], v[194:197], v[96:99]
	v_mfma_f32_16x16x32_bf16 v[84:87], v[170:173], v[206:209], v[84:87]
	v_mfma_f32_16x16x32_bf16 v[80:83], v[178:181], v[206:209], v[80:83]
	v_mfma_f32_16x16x32_bf16 v[68:71], v[170:173], v[214:217], v[68:71]
	v_mfma_f32_16x16x32_bf16 v[64:67], v[178:181], v[214:217], v[64:67]
	s_setprio 0
	s_barrier
	s_add_i32 s52, s43, s34
	v_lshl_add_u64 v[202:203], s[24:25], 0, v[130:131]
	s_mov_b32 m0, s52
	ds_read_b128 v[182:185], v149 offset:16384
	ds_read_b128 v[186:189], v149 offset:17408
	ds_read_b128 v[190:193], v149 offset:18432
	ds_read_b128 v[194:197], v149 offset:19456
	ds_read_b128 v[198:201], v149 offset:20480
	ds_read_b128 v[206:209], v149 offset:21504
	ds_read_b128 v[210:213], v149 offset:22528
	ds_read_b128 v[214:217], v149 offset:23552
	global_load_lds_dwordx4 v130, s[24:25]
	s_add_i32 m0, s52, 0x2000
	s_add_u32 s52, s24, 0x40000
	v_lshl_add_u64 v[218:219], s[24:25], 0, v[134:135]
	s_addc_u32 s53, s25, 0
	s_add_i32 s54, s44, s34
	global_load_lds_dwordx4 v134, s[24:25]
	s_mov_b32 m0, s54
	v_lshl_add_u64 v[222:223], s[26:27], 0, v[132:133]
	global_load_lds_dwordx4 v130, s[52:53]
	s_add_i32 m0, s54, 0x2000
	s_nop 0
	global_load_lds_dwordx4 v134, s[52:53]
	v_lshl_add_u64 v[220:221], s[26:27], 0, v[128:129]
	s_mov_b32 m0, s21
	s_nop 0
	global_load_lds_dwordx4 v128, s[26:27]
	s_mov_b32 m0, s35
	s_nop 0
	global_load_lds_dwordx4 v132, s[26:27]
	s_waitcnt vmcnt(8)
	s_waitcnt lgkmcnt(0)
	s_barrier
	s_setprio 1
	s_waitcnt lgkmcnt(0)
	v_mfma_f32_16x16x32_bf16 v[60:63], v[150:153], v[182:185], v[60:63]
	v_mfma_f32_16x16x32_bf16 v[56:59], v[158:161], v[182:185], v[56:59]
	v_mfma_f32_16x16x32_bf16 v[44:47], v[150:153], v[190:193], v[44:47]
	v_mfma_f32_16x16x32_bf16 v[40:43], v[158:161], v[190:193], v[40:43]
	v_mfma_f32_16x16x32_bf16 v[28:31], v[150:153], v[198:201], v[28:31]
	v_mfma_f32_16x16x32_bf16 v[24:27], v[158:161], v[198:201], v[24:27]
	v_mfma_f32_16x16x32_bf16 v[12:15], v[150:153], v[210:213], v[12:15]
	v_mfma_f32_16x16x32_bf16 v[8:11], v[158:161], v[210:213], v[8:11]
	v_mfma_f32_16x16x32_bf16 v[60:63], v[154:157], v[186:189], v[60:63]
	v_mfma_f32_16x16x32_bf16 v[56:59], v[162:165], v[186:189], v[56:59]
	v_mfma_f32_16x16x32_bf16 v[44:47], v[154:157], v[194:197], v[44:47]
	v_mfma_f32_16x16x32_bf16 v[40:43], v[162:165], v[194:197], v[40:43]
	v_mfma_f32_16x16x32_bf16 v[28:31], v[154:157], v[206:209], v[28:31]
	v_mfma_f32_16x16x32_bf16 v[24:27], v[162:165], v[206:209], v[24:27]
	v_mfma_f32_16x16x32_bf16 v[12:15], v[154:157], v[214:217], v[12:15]
	v_mfma_f32_16x16x32_bf16 v[8:11], v[162:165], v[214:217], v[8:11]
	s_setprio 0
	s_setprio 1
	v_mfma_f32_16x16x32_bf16 v[52:55], v[166:169], v[182:185], v[52:55]
	v_mfma_f32_16x16x32_bf16 v[48:51], v[174:177], v[182:185], v[48:51]
	v_mfma_f32_16x16x32_bf16 v[36:39], v[166:169], v[190:193], v[36:39]
	v_mfma_f32_16x16x32_bf16 v[32:35], v[174:177], v[190:193], v[32:35]
	v_mfma_f32_16x16x32_bf16 v[20:23], v[166:169], v[198:201], v[20:23]
	v_mfma_f32_16x16x32_bf16 v[16:19], v[174:177], v[198:201], v[16:19]
	v_mfma_f32_16x16x32_bf16 v[4:7], v[166:169], v[210:213], v[4:7]
	v_mfma_f32_16x16x32_bf16 v[0:3], v[174:177], v[210:213], v[0:3]
	v_mfma_f32_16x16x32_bf16 v[52:55], v[170:173], v[186:189], v[52:55]
	v_mfma_f32_16x16x32_bf16 v[48:51], v[178:181], v[186:189], v[48:51]
	v_mfma_f32_16x16x32_bf16 v[36:39], v[170:173], v[194:197], v[36:39]
	v_mfma_f32_16x16x32_bf16 v[32:35], v[178:181], v[194:197], v[32:35]
	v_mfma_f32_16x16x32_bf16 v[20:23], v[170:173], v[206:209], v[20:23]
	v_mfma_f32_16x16x32_bf16 v[16:19], v[178:181], v[206:209], v[16:19]
	v_mfma_f32_16x16x32_bf16 v[4:7], v[170:173], v[214:217], v[4:7]
	v_mfma_f32_16x16x32_bf16 v[0:3], v[178:181], v[214:217], v[0:3]
	s_setprio 0
	s_barrier
	s_add_i32 s52, 0, 0x18000
	s_add_i32 s53, 0, 0x1c000
	v_add_u32_e32 v162, s52, v145
	v_add_u32_e32 v178, s53, v145
	ds_read_b128 v[150:153], v162
	ds_read_b128 v[154:157], v162 offset:1024
	ds_read_b128 v[158:161], v162 offset:2048
	ds_read_b128 v[162:165], v162 offset:3072
	ds_read_b128 v[166:169], v178
	ds_read_b128 v[170:173], v178 offset:1024
	ds_read_b128 v[174:177], v178 offset:2048
	ds_read_b128 v[178:181], v178 offset:3072
	s_add_u32 s26, s26, 0x40000
	s_addc_u32 s27, s27, 0
	s_mov_b32 m0, s36
	ds_read_b128 v[182:185], v149 offset:32768
	ds_read_b128 v[186:189], v149 offset:33792
	ds_read_b128 v[190:193], v149 offset:34816
	ds_read_b128 v[194:197], v149 offset:35840
	ds_read_b128 v[198:201], v149 offset:36864
	ds_read_b128 v[206:209], v149 offset:37888
	ds_read_b128 v[210:213], v149 offset:38912
	ds_read_b128 v[214:217], v149 offset:39936
	global_load_lds_dwordx4 v128, s[26:27]
	s_mov_b32 m0, s37
	s_nop 0
	global_load_lds_dwordx4 v132, s[26:27]
	s_waitcnt vmcnt(8)
	s_waitcnt lgkmcnt(0)
	s_barrier
	s_setprio 1
	s_waitcnt lgkmcnt(0)
	v_mfma_f32_16x16x32_bf16 v[124:127], v[150:153], v[182:185], v[124:127]
	v_mfma_f32_16x16x32_bf16 v[120:123], v[158:161], v[182:185], v[120:123]
	v_mfma_f32_16x16x32_bf16 v[108:111], v[150:153], v[190:193], v[108:111]
	v_mfma_f32_16x16x32_bf16 v[104:107], v[158:161], v[190:193], v[104:107]
	v_mfma_f32_16x16x32_bf16 v[92:95], v[150:153], v[198:201], v[92:95]
	v_mfma_f32_16x16x32_bf16 v[88:91], v[158:161], v[198:201], v[88:91]
	v_mfma_f32_16x16x32_bf16 v[76:79], v[150:153], v[210:213], v[76:79]
	v_mfma_f32_16x16x32_bf16 v[72:75], v[158:161], v[210:213], v[72:75]
	v_mfma_f32_16x16x32_bf16 v[124:127], v[154:157], v[186:189], v[124:127]
	v_mfma_f32_16x16x32_bf16 v[120:123], v[162:165], v[186:189], v[120:123]
	v_mfma_f32_16x16x32_bf16 v[108:111], v[154:157], v[194:197], v[108:111]
	v_mfma_f32_16x16x32_bf16 v[104:107], v[162:165], v[194:197], v[104:107]
	v_mfma_f32_16x16x32_bf16 v[92:95], v[154:157], v[206:209], v[92:95]
	v_mfma_f32_16x16x32_bf16 v[88:91], v[162:165], v[206:209], v[88:91]
	v_mfma_f32_16x16x32_bf16 v[76:79], v[154:157], v[214:217], v[76:79]
	v_mfma_f32_16x16x32_bf16 v[72:75], v[162:165], v[214:217], v[72:75]
	s_setprio 0
	s_setprio 1
	v_mfma_f32_16x16x32_bf16 v[116:119], v[166:169], v[182:185], v[116:119]
	v_mfma_f32_16x16x32_bf16 v[112:115], v[174:177], v[182:185], v[112:115]
	v_mfma_f32_16x16x32_bf16 v[100:103], v[166:169], v[190:193], v[100:103]
	v_mfma_f32_16x16x32_bf16 v[96:99], v[174:177], v[190:193], v[96:99]
	v_mfma_f32_16x16x32_bf16 v[84:87], v[166:169], v[198:201], v[84:87]
	v_mfma_f32_16x16x32_bf16 v[80:83], v[174:177], v[198:201], v[80:83]
	v_mfma_f32_16x16x32_bf16 v[68:71], v[166:169], v[210:213], v[68:71]
	v_mfma_f32_16x16x32_bf16 v[64:67], v[174:177], v[210:213], v[64:67]
	v_mfma_f32_16x16x32_bf16 v[116:119], v[170:173], v[186:189], v[116:119]
	v_mfma_f32_16x16x32_bf16 v[112:115], v[178:181], v[186:189], v[112:115]
	v_mfma_f32_16x16x32_bf16 v[100:103], v[170:173], v[194:197], v[100:103]
	v_mfma_f32_16x16x32_bf16 v[96:99], v[178:181], v[194:197], v[96:99]
	v_mfma_f32_16x16x32_bf16 v[84:87], v[170:173], v[206:209], v[84:87]
	v_mfma_f32_16x16x32_bf16 v[80:83], v[178:181], v[206:209], v[80:83]
	v_mfma_f32_16x16x32_bf16 v[68:71], v[170:173], v[214:217], v[68:71]
	v_mfma_f32_16x16x32_bf16 v[64:67], v[178:181], v[214:217], v[64:67]
	s_setprio 0
	s_barrier
	s_add_i32 s26, s52, s34
	v_lshl_add_u64 v[202:203], v[202:203], 0, s[8:9]
	s_mov_b32 m0, s26
	ds_read_b128 v[182:185], v149 offset:49152
	ds_read_b128 v[186:189], v149 offset:50176
	ds_read_b128 v[190:193], v149 offset:51200
	ds_read_b128 v[194:197], v149 offset:52224
	ds_read_b128 v[198:201], v149 offset:53248
	ds_read_b128 v[206:209], v149 offset:54272
	ds_read_b128 v[210:213], v149 offset:55296
	ds_read_b128 v[214:217], v149 offset:56320
	global_load_lds_dwordx4 v[202:203], off
	s_add_i32 m0, s26, 0x2000
	s_add_u32 s24, s24, 0x40080
	v_lshl_add_u64 v[202:203], v[218:219], 0, s[8:9]
	s_addc_u32 s25, s25, 0
	s_add_i32 s26, s53, s34
	global_load_lds_dwordx4 v[202:203], off
	s_mov_b32 m0, s26
	s_nop 0
	global_load_lds_dwordx4 v130, s[24:25]
	s_add_i32 m0, s26, 0x2000
	s_nop 0
	global_load_lds_dwordx4 v134, s[24:25]
	v_lshl_add_u64 v[202:203], v[220:221], 0, s[8:9]
	s_mov_b32 m0, s40
	s_nop 0
	global_load_lds_dwordx4 v[202:203], off
	v_lshl_add_u64 v[202:203], v[222:223], 0, s[8:9]
	s_mov_b32 m0, s41
	s_nop 0
	global_load_lds_dwordx4 v[202:203], off
	s_waitcnt vmcnt(8)
	s_waitcnt lgkmcnt(0)
	s_barrier
	s_setprio 1
	s_waitcnt lgkmcnt(0)
	v_mfma_f32_16x16x32_bf16 v[60:63], v[150:153], v[182:185], v[60:63]
	v_mfma_f32_16x16x32_bf16 v[56:59], v[158:161], v[182:185], v[56:59]
	v_mfma_f32_16x16x32_bf16 v[44:47], v[150:153], v[190:193], v[44:47]
	v_mfma_f32_16x16x32_bf16 v[40:43], v[158:161], v[190:193], v[40:43]
	v_mfma_f32_16x16x32_bf16 v[28:31], v[150:153], v[198:201], v[28:31]
	v_mfma_f32_16x16x32_bf16 v[24:27], v[158:161], v[198:201], v[24:27]
	v_mfma_f32_16x16x32_bf16 v[12:15], v[150:153], v[210:213], v[12:15]
	v_mfma_f32_16x16x32_bf16 v[8:11], v[158:161], v[210:213], v[8:11]
	v_mfma_f32_16x16x32_bf16 v[60:63], v[154:157], v[186:189], v[60:63]
	v_mfma_f32_16x16x32_bf16 v[56:59], v[162:165], v[186:189], v[56:59]
	v_mfma_f32_16x16x32_bf16 v[44:47], v[154:157], v[194:197], v[44:47]
	v_mfma_f32_16x16x32_bf16 v[40:43], v[162:165], v[194:197], v[40:43]
	v_mfma_f32_16x16x32_bf16 v[28:31], v[154:157], v[206:209], v[28:31]
	v_mfma_f32_16x16x32_bf16 v[24:27], v[162:165], v[206:209], v[24:27]
	v_mfma_f32_16x16x32_bf16 v[12:15], v[154:157], v[214:217], v[12:15]
	v_mfma_f32_16x16x32_bf16 v[8:11], v[162:165], v[214:217], v[8:11]
	s_setprio 0
	s_setprio 1
	v_mfma_f32_16x16x32_bf16 v[52:55], v[166:169], v[182:185], v[52:55]
	v_mfma_f32_16x16x32_bf16 v[48:51], v[174:177], v[182:185], v[48:51]
	v_mfma_f32_16x16x32_bf16 v[36:39], v[166:169], v[190:193], v[36:39]
	v_mfma_f32_16x16x32_bf16 v[32:35], v[174:177], v[190:193], v[32:35]
	v_mfma_f32_16x16x32_bf16 v[20:23], v[166:169], v[198:201], v[20:23]
	v_mfma_f32_16x16x32_bf16 v[16:19], v[174:177], v[198:201], v[16:19]
	v_mfma_f32_16x16x32_bf16 v[4:7], v[166:169], v[210:213], v[4:7]
	v_mfma_f32_16x16x32_bf16 v[0:3], v[174:177], v[210:213], v[0:3]
	v_mfma_f32_16x16x32_bf16 v[52:55], v[170:173], v[186:189], v[52:55]
	v_mfma_f32_16x16x32_bf16 v[48:51], v[178:181], v[186:189], v[48:51]
	v_mfma_f32_16x16x32_bf16 v[36:39], v[170:173], v[194:197], v[36:39]
	v_mfma_f32_16x16x32_bf16 v[32:35], v[178:181], v[194:197], v[32:35]
	v_mfma_f32_16x16x32_bf16 v[20:23], v[170:173], v[206:209], v[20:23]
	v_mfma_f32_16x16x32_bf16 v[16:19], v[178:181], v[206:209], v[16:19]
	v_mfma_f32_16x16x32_bf16 v[4:7], v[170:173], v[214:217], v[4:7]
	v_mfma_f32_16x16x32_bf16 v[0:3], v[178:181], v[214:217], v[0:3]
	s_setprio 0
	s_barrier
	s_add_i32 s51, s51, 2
	s_add_u32 s22, s22, 0x100
	s_addc_u32 s23, s23, 0
	s_add_u32 s49, s49, 0x100
	s_addc_u32 s50, s50, 0
	s_cmp_gt_u32 s51, 13
	s_cbranch_scc0 .LBB0_1243
	v_mul_f32_e32 v151, 0xbfb8aa3b, v124
	v_mul_f32_e32 v154, 0xbfb8aa3b, v120
	v_exp_f32_e32 v151, v151
	v_exp_f32_e32 v155, v154
	v_mul_f32_e32 v154, 0xbfb8aa3b, v125
	v_exp_f32_e32 v156, v154
	v_add_f32_e32 v151, 1.0, v151
	v_rcp_f32_e32 v154, v151
	v_add_f32_e32 v151, 1.0, v155
	v_add_f32_e32 v155, 1.0, v156
	v_rcp_f32_e32 v155, v155
	v_mul_f32_e32 v156, 0xbfb8aa3b, v121
	v_exp_f32_e32 v157, v156
	v_rcp_f32_e32 v156, v151
	v_pk_mul_f32 v[124:125], v[124:125], v[154:155]
	v_mul_f32_e32 v151, 0xbfb8aa3b, v127
	v_pk_mul_f32 v[116:117], v[124:125], v[116:117]
	v_add_f32_e32 v124, 1.0, v157
	v_mul_f32_e32 v125, 0xbfb8aa3b, v122
	v_rcp_f32_e32 v157, v124
	v_mul_f32_e32 v124, 0xbfb8aa3b, v126
	v_exp_f32_e32 v125, v125
	v_exp_f32_e32 v124, v124
	v_exp_f32_e32 v151, v151
	v_mul_f32_e32 v154, 0xbfb8aa3b, v123
	v_exp_f32_e32 v155, v154
	v_add_f32_e32 v125, 1.0, v125
	v_add_f32_e32 v124, 1.0, v124
	v_rcp_f32_e32 v154, v125
	v_add_f32_e32 v125, 1.0, v151
	v_rcp_f32_e32 v124, v124
	v_rcp_f32_e32 v125, v125
	v_add_f32_e32 v151, 1.0, v155
	v_rcp_f32_e32 v155, v151
	v_pk_mul_f32 v[120:121], v[120:121], v[156:157]
	v_lshl_or_b32 v152, s46, 7, v146
	v_pk_mul_f32 v[112:113], v[120:121], v[112:113]
	v_pk_mul_f32 v[120:121], v[126:127], v[124:125]
	v_lshl_add_u32 v150, s20, 8, v144
	v_pk_mul_f32 v[118:119], v[120:121], v[118:119]
	v_pk_mul_f32 v[120:121], v[122:123], v[154:155]
	v_ashrrev_i32_e32 v153, 31, v152
	v_pk_mul_f32 v[114:115], v[120:121], v[114:115]
	v_cvt_pk_bf16_f32 v116, v116, v117
	v_cvt_pk_bf16_f32 v117, v118, v119
	v_cvt_pk_bf16_f32 v118, v112, v113
	v_mov_b64_e32 v[112:113], s[6:7]
	v_cvt_pk_bf16_f32 v119, v114, v115
	v_mad_i64_i32 v[120:121], s[22:23], v150, s45, v[112:113]
	v_lshlrev_b64 v[114:115], 1, v[152:153]
	v_lshl_add_u64 v[120:121], v[120:121], 0, v[114:115]
	s_and_b64 vcc, exec, s[10:11]
	s_cbranch_vccz .LBB0_1246
	s_barrier
